# baseline (speedup 1.0000x reference)
; #define RUNPH(n) { run_phase(p, (n), smem); grid.sync(); }
; __global__ void __launch_bounds__(256, 2) mega(Params p) {
;   extern __shared__ __attribute__((aligned(16))) char smem[];
;   cg::grid_group grid = cg::this_grid();
;   RUNPH(0) RUNPH(1) RUNPH(2) RUNPH(3) RUNPH(4) RUNPH(5) RUNPH(6) RUNPH(7) RUNPH(8)
.Lgb0_go:
	s_getreg_b32 s0, hwreg(HW_REG_XCC_ID, 0, 4)
	s_and_b32 s0, s0, 15
	s_lshl_b32 s0, 1, s0
	s_and_b32 s1, s98, 7
	s_lshl_b32 s1, s1, 8
	s_add_u32 s1, s1, 0x2000
	v_mov_b32_e32 v0, s1
	v_mov_b32_e32 v1, s0
	global_atomic_or v0, v1, s[6:7]
	buffer_wbl2 sc1
	s_waitcnt vmcnt(0)
	s_and_b32 s0, s98, 7
	s_sub_u32 s1, s99, s0
	s_add_u32 s1, s1, 7
	s_lshr_b32 s1, s1, 3
	s_lshl_b32 s0, s0, 8
	v_mov_b32_e32 v2, s0
	v_mov_b32_e32 v0, 0
	v_mov_b32_e32 v1, 1
	s_mov_b32 s8, 0
	global_atomic_add v3, v2, v1, s[6:7] sc0
	s_waitcnt vmcnt(0)
	v_readfirstlane_b32 s0, v3
	s_add_u32 s0, s0, 1
	s_cmp_eq_u32 s0, s1
	s_cbranch_scc0 .Lgb0_pollg
	s_add_u32 s6, s6, 0x1000
	s_addc_u32 s7, s7, 0
	global_atomic_add v3, v0, v1, s[6:7] sc0
	s_min_u32 s1, s99, 8
	s_waitcnt vmcnt(0)
	v_readfirstlane_b32 s0, v3
	s_add_u32 s0, s0, 1
	s_cmp_eq_u32 s0, s1
	s_cbranch_scc0 .Lgb0_pollt
	global_atomic_add v0, v1, s[6:7] offset:256
	s_branch .Lgb0_relg

; __device__ __forceinline__ ushort_t* wsb(const Params& p, size_t off) { return (ushort_t*)(p.ws + off); }
; __device__ __forceinline__ ushort_t* wts(const Params& p, size_t eoff) { return (ushort_t*)(p.ws + OFF_W) + eoff; }
; __device__ __forceinline__ int opaque_tid() { int t = threadIdx.x; asm volatile("" : "+v"(t)); return t; }
; #define TILE_LOOP2(NTV) for (int q_ = blockIdx.x >> 3, mt = 0, nt = 0; tile_coords(q_, (NTV), mt, nt, 256); q_ += gridDim.x >> 3)
; #define RUNPH(n) { run_phase(p, (n), smem); grid.sync(); }
; __device__ __forceinline__ void phase_fox_inproj(const Params& p, char* smem) {
;   const int tid = opaque_tid(), row = tid >> 1, hf = tid & 1;
;   float* Cs = (float*)smem;
;   const ushort_t* xb = wsb(p, OFF_XB);
;   ushort_t* Qb = wsb(p, OFF_P + 0 * SLOT);
;   ushort_t* Kb = wsb(p, OFF_P + 1 * SLOT);
;   ushort_t* Vt = wsb(p, OFF_P + 2 * SLOT);
;   ushort_t* G = wsb(p, OFF_P + 3 * SLOT);
;   float* LF = (float*)(p.ws + OFF_LF);
;   const int NT = 33;
;   TILE_LOOP2(NT) {
;     f32x4 acc[8][4];
;     gemm_core256<false>(xb + (long)mt * 256 * 1024, 1024, wts(p, W_FOX_IN) + (long)nt * 128 * 1024, 1024, 1024, smem, acc, mt * 256, wsb(p, OFF_ZERO));
; #pragma unroll 1
;     for (int half = 0; half < 2; ++half) {
;     const int row0 = mt * 256 + half * 128;
;     if (((opaque_tid() >> 7) & 1) == half) { if (nt >= 16 && nt < 24) stage_acc8_T(Cs, acc); else stage_acc8(Cs, acc); }
;     __syncthreads();
;     const long tok = row0 + row;
;     const float* cs = Cs + row * CS_LD + hf * 64;
;     if (nt < 8) {
;       store_tile(Qb + (long)row0 * 1024 + nt * 128, 1024, Cs, [](float v, int, int) { return v * QSCALE_F; });
; __global__ void __launch_bounds__(256, 2) mega(Params p) {
;   extern __shared__ __attribute__((aligned(16))) char smem[];
;   cg::grid_group grid = cg::this_grid();
;   RUNPH(0) RUNPH(1) RUNPH(2) RUNPH(3) RUNPH(4) RUNPH(5) RUNPH(6) RUNPH(7) RUNPH(8)
.Lgb0_done:
	s_add_u32 s6, s30, 0x3eb3a000
	s_addc_u32 s7, s31, 0
	s_and_b32 s1, s98, 7
	s_lshl_b32 s1, s1, 8
	v_mov_b32_e32 v0, s1
	global_load_dword v3, v0, s[6:7] sc1
	s_waitcnt vmcnt(0)
	v_readfirstlane_b32 s0, v3
	s_bcnt1_i32_b32 s0, s0
	s_cmp_eq_u32 s0, 1
	s_cselect_b32 s100, 1, 0
	buffer_inv sc1
	s_waitcnt vmcnt(0)
.LBB0_119:
	s_or_b64 exec, exec, s[4:5]
	s_add_u32 s48, s30, 0x30000000
	s_addc_u32 s49, s31, 0
	s_add_u32 s46, s30, 0x10000000
	s_addc_u32 s47, s31, 0
	s_add_u32 s16, s30, 0x3b740000
	v_mov_b32_e32 v0, v140
	s_addc_u32 s17, s31, 0
	s_lshr_b32 s94, s96, 3
	s_and_b32 s93, s96, 7
	s_barrier
	s_add_u32 s1, s30, 0x38000000
	v_ashrrev_i32_e32 v143, 1, v0
	v_lshlrev_b32_e32 v0, 2, v0
	v_writelane_b32 v225, s1, 18
	s_addc_u32 s1, s31, 0
	v_and_b32_e32 v145, 4, v0
	s_movk_i32 s0, 0x210
	v_writelane_b32 v225, s1, 13
	v_mul_lo_u32 v1, v143, s0
	v_lshlrev_b32_e32 v0, 2, v145
	v_readlane_b32 s2, v225, 2
	s_mov_b32 s5, 0
	v_add3_u32 v154, 0, v1, v0
	v_mov_b32_e32 v1, 0
	v_readlane_b32 s3, v225, 3
	v_or_b32_e32 v155, 1, v145
	v_or_b32_e32 v156, 2, v145
	v_or_b32_e32 v157, 3, v145
	v_lshl_add_u64 v[136:137], s[44:45], 0, v[0:1]
	s_lshr_b32 s95, s2, 3
	s_movk_i32 s1, 0xf800
	s_mov_b64 s[6:7], 0x20000
	s_mov_b64 s[8:9], 0x20040
	s_add_i32 s33, 0, 0x10000
	s_movk_i32 s3, 0x84
	s_mov_b32 s23, 0xbfb8aa3b
	s_mov_b32 s35, 0x3f2aaaab
	v_mov_b32_e32 v158, 0x3ecc95a3
	s_mov_b32 s82, 0x3f317218
	s_mov_b32 s83, 0x7f800000
	s_mov_b32 s84, 0x33800000
	s_mov_b32 s85, 0x20000
	v_mov_b32_e32 v159, 0x7f800000
	v_mov_b32_e32 v160, 0x7fc00000
	v_mov_b32_e32 v161, 0xff800000
	s_mov_b32 s86, s94
	s_mov_b64 s[10:11], 0x30020100
	s_mov_b64 s[12:13], 0x30040100
	s_mov_b64 s[14:15], 0x30060100
	s_mov_b64 s[18:19], 0x38000100
	s_mov_b64 s[20:21], 0x38020100
	s_mov_b32 s22, 0x3e0293ee
	s_mov_b32 s26, s5
	s_mov_b32 s42, s5
	s_branch .LBB0_122

; __device__ __forceinline__ int opaque_tid() { int t = threadIdx.x; asm volatile("" : "+v"(t)); return t; }
; template <class F>
; __device__ __forceinline__ void store_tile(ushort_t* dst, long ld, const float* Cs, F f) {
;   const int tid = opaque_tid(), c16 = tid & 15, rgrp = tid >> 4;
; #pragma unroll
;   for (int it = 0; it < 8; ++it) {
;     const int row = it * 16 + rgrp;
;     const float4 v0 = *(const float4*)(Cs + row * CS_LD + c16 * 8), v1 = *(const float4*)(Cs + row * CS_LD + c16 * 8 + 4);
;     const int c = c16 * 8;
;     u32x4 o;
;     o.x = pack2(f(v0.x, row, c), f(v0.y, row, c + 1));
;     o.y = pack2(f(v0.z, row, c + 2), f(v0.w, row, c + 3));
;     o.z = pack2(f(v1.x, row, c + 4), f(v1.y, row, c + 5));
;     o.w = pack2(f(v1.z, row, c + 6), f(v1.w, row, c + 7));
;     *(u32x4*)(dst + (long)row * ld + c) = o;
;   }
; }
; __device__ __forceinline__ void phase_fox_inproj(const Params& p, char* smem) {
;     ...
;       store_tile(Qb + (long)row0 * 1024 + nt * 128, 1024, Cs, [](float v, int, int) { return v * QSCALE_F; });
.LBB0_167:
	s_andn2_b64 vcc, exec, s[80:81]
	s_cbranch_vccnz .LBB0_147
	v_mov_b32_e32 v0, v140
	s_ashr_i32 s77, s76, 31
	s_lshl_b64 s[76:77], s[76:77], 11
	v_ashrrev_i32_e32 v166, 4, v0
	v_lshlrev_b32_e32 v0, 3, v0
	s_add_u32 s76, s4, s76
	v_and_b32_e32 v0, 0x78, v0
	s_addc_u32 s77, s90, s77
	v_lshlrev_b32_e32 v132, 2, v0
	v_lshlrev_b32_e32 v0, 1, v0
	v_lshl_add_u64 v[168:169], s[76:77], 0, v[0:1]
	v_mul_lo_u32 v0, v166, s0
	v_add3_u32 v0, 0, v132, v0
	ds_read_b128 v[132:135], v0
	ds_read_b128 v[150:153], v0 offset:16
	v_ashrrev_i32_e32 v167, 31, v166
	s_mov_b32 s2, 0x8000
	s_waitcnt lgkmcnt(1)
	v_pk_mul_f32 v[132:133], v[132:133], s[22:23] op_sel_hi:[1,0]
	s_nop 0
	v_cvt_pk_bf16_f32 v162, v132, v133
	v_pk_mul_f32 v[132:133], v[134:135], s[22:23] op_sel_hi:[1,0]
	s_nop 0
	v_cvt_pk_bf16_f32 v163, v132, v133
	s_waitcnt lgkmcnt(0)
	v_pk_mul_f32 v[132:133], v[150:151], s[22:23] op_sel_hi:[1,0]
	s_nop 0
	v_cvt_pk_bf16_f32 v164, v132, v133
	v_pk_mul_f32 v[132:133], v[152:153], s[22:23] op_sel_hi:[1,0]
	ds_read_b128 v[150:153], v0 offset:8448
	v_cvt_pk_bf16_f32 v165, v132, v133
	v_lshlrev_b64 v[132:133], 11, v[166:167]
	v_lshl_add_u64 v[132:133], v[168:169], 0, v[132:133]
	global_store_dwordx4 v[132:133], v[162:165], off
	ds_read_b128 v[162:165], v0 offset:8464
	s_waitcnt lgkmcnt(1)
	v_pk_mul_f32 v[134:135], v[150:151], s[22:23] op_sel_hi:[1,0]
	s_nop 0
	v_cvt_pk_bf16_f32 v150, v134, v135
	v_pk_mul_f32 v[134:135], v[152:153], s[22:23] op_sel_hi:[1,0]
	s_nop 0
	v_cvt_pk_bf16_f32 v151, v134, v135
	s_waitcnt lgkmcnt(0)
	v_pk_mul_f32 v[134:135], v[162:163], s[22:23] op_sel_hi:[1,0]
	s_nop 0
	v_cvt_pk_bf16_f32 v152, v134, v135
	v_pk_mul_f32 v[134:135], v[164:165], s[22:23] op_sel_hi:[1,0]
	ds_read_b128 v[162:165], v0 offset:16912
	v_cvt_pk_bf16_f32 v153, v134, v135
	v_add_co_u32_e32 v134, vcc, s2, v132
	s_mov_b32 s2, 0x10000
	s_nop 0
	v_addc_co_u32_e32 v135, vcc, 0, v133, vcc
	global_store_dwordx4 v[134:135], v[150:153], off
	ds_read_b128 v[150:153], v0 offset:16896
	s_waitcnt lgkmcnt(0)
	v_pk_mul_f32 v[134:135], v[150:151], s[22:23] op_sel_hi:[1,0]
	s_nop 0
	v_cvt_pk_bf16_f32 v150, v134, v135
	v_pk_mul_f32 v[134:135], v[152:153], s[22:23] op_sel_hi:[1,0]
	s_nop 0
	v_cvt_pk_bf16_f32 v151, v134, v135
	v_pk_mul_f32 v[134:135], v[162:163], s[22:23] op_sel_hi:[1,0]
	s_nop 0
	v_cvt_pk_bf16_f32 v152, v134, v135
	v_pk_mul_f32 v[134:135], v[164:165], s[22:23] op_sel_hi:[1,0]
	ds_read_b128 v[162:165], v0 offset:25360
	v_cvt_pk_bf16_f32 v153, v134, v135
	v_add_co_u32_e32 v134, vcc, s2, v132
	s_mov_b32 s2, 0x18000
	s_nop 0
	v_addc_co_u32_e32 v135, vcc, 0, v133, vcc
	global_store_dwordx4 v[134:135], v[150:153], off
	ds_read_b128 v[150:153], v0 offset:25344
	s_waitcnt lgkmcnt(0)
	v_pk_mul_f32 v[134:135], v[150:151], s[22:23] op_sel_hi:[1,0]
	s_nop 0
	v_cvt_pk_bf16_f32 v150, v134, v135
	v_pk_mul_f32 v[134:135], v[152:153], s[22:23] op_sel_hi:[1,0]
	s_nop 0
	v_cvt_pk_bf16_f32 v151, v134, v135
	v_pk_mul_f32 v[134:135], v[162:163], s[22:23] op_sel_hi:[1,0]
	s_nop 0
	v_cvt_pk_bf16_f32 v152, v134, v135
	v_pk_mul_f32 v[134:135], v[164:165], s[22:23] op_sel_hi:[1,0]
	ds_read_b128 v[162:165], v0 offset:33808
	v_cvt_pk_bf16_f32 v153, v134, v135
	v_add_co_u32_e32 v134, vcc, s2, v132
	s_mov_b32 s2, 0x28000
	s_nop 0
	v_addc_co_u32_e32 v135, vcc, 0, v133, vcc
	global_store_dwordx4 v[134:135], v[150:153], off
	ds_read_b128 v[150:153], v0 offset:33792
	s_waitcnt lgkmcnt(0)
	v_pk_mul_f32 v[134:135], v[150:151], s[22:23] op_sel_hi:[1,0]
	s_nop 0
	v_cvt_pk_bf16_f32 v150, v134, v135
	v_pk_mul_f32 v[134:135], v[152:153], s[22:23] op_sel_hi:[1,0]
	s_nop 0
	v_cvt_pk_bf16_f32 v151, v134, v135
	v_pk_mul_f32 v[134:135], v[162:163], s[22:23] op_sel_hi:[1,0]
	s_nop 0
	v_cvt_pk_bf16_f32 v152, v134, v135
	v_pk_mul_f32 v[134:135], v[164:165], s[22:23] op_sel_hi:[1,0]
	ds_read_b128 v[162:165], v0 offset:42256
	v_cvt_pk_bf16_f32 v153, v134, v135
	v_add_co_u32_e32 v134, vcc, s85, v132
	s_nop 1
	v_addc_co_u32_e32 v135, vcc, 0, v133, vcc
	global_store_dwordx4 v[134:135], v[150:153], off
	ds_read_b128 v[150:153], v0 offset:42240
	s_waitcnt lgkmcnt(0)
	v_pk_mul_f32 v[134:135], v[150:151], s[22:23] op_sel_hi:[1,0]
	s_nop 0
	v_cvt_pk_bf16_f32 v150, v134, v135
	v_pk_mul_f32 v[134:135], v[152:153], s[22:23] op_sel_hi:[1,0]
	s_nop 0
	v_cvt_pk_bf16_f32 v151, v134, v135
	v_pk_mul_f32 v[134:135], v[162:163], s[22:23] op_sel_hi:[1,0]
	s_nop 0
	v_cvt_pk_bf16_f32 v152, v134, v135
	v_pk_mul_f32 v[134:135], v[164:165], s[22:23] op_sel_hi:[1,0]
	s_nop 0
	v_cvt_pk_bf16_f32 v153, v134, v135
	v_add_co_u32_e32 v134, vcc, s2, v132
	s_mov_b32 s2, 0x30000
	s_nop 0
	v_addc_co_u32_e32 v135, vcc, 0, v133, vcc
	global_store_dwordx4 v[134:135], v[150:153], off
	ds_read_b128 v[150:153], v0 offset:50688
	ds_read_b128 v[162:165], v0 offset:50704
	s_waitcnt lgkmcnt(1)
	v_pk_mul_f32 v[134:135], v[150:151], s[22:23] op_sel_hi:[1,0]
	s_nop 0
	v_cvt_pk_bf16_f32 v150, v134, v135
	v_pk_mul_f32 v[134:135], v[152:153], s[22:23] op_sel_hi:[1,0]
	s_nop 0
	v_cvt_pk_bf16_f32 v151, v134, v135
	s_waitcnt lgkmcnt(0)
	v_pk_mul_f32 v[134:135], v[162:163], s[22:23] op_sel_hi:[1,0]
	s_nop 0
	v_cvt_pk_bf16_f32 v152, v134, v135
	v_pk_mul_f32 v[134:135], v[164:165], s[22:23] op_sel_hi:[1,0]
	ds_read_b128 v[162:165], v0 offset:59152
	v_cvt_pk_bf16_f32 v153, v134, v135
	v_add_co_u32_e32 v134, vcc, s2, v132
	s_nop 1
	v_addc_co_u32_e32 v135, vcc, 0, v133, vcc
	global_store_dwordx4 v[134:135], v[150:153], off
	ds_read_b128 v[150:153], v0 offset:59136
	v_add_co_u32_e32 v132, vcc, 0x38000, v132
	s_waitcnt lgkmcnt(0)
	v_pk_mul_f32 v[134:135], v[150:151], s[22:23] op_sel_hi:[1,0]
	s_nop 0
	v_cvt_pk_bf16_f32 v150, v134, v135
	v_pk_mul_f32 v[134:135], v[152:153], s[22:23] op_sel_hi:[1,0]
	v_addc_co_u32_e32 v133, vcc, 0, v133, vcc
	v_cvt_pk_bf16_f32 v151, v134, v135
	v_pk_mul_f32 v[134:135], v[162:163], s[22:23] op_sel_hi:[1,0]
	s_nop 0
	v_cvt_pk_bf16_f32 v152, v134, v135
	v_pk_mul_f32 v[134:135], v[164:165], s[22:23] op_sel_hi:[1,0]
	s_nop 0
	v_cvt_pk_bf16_f32 v153, v134, v135
	global_store_dwordx4 v[132:133], v[150:153], off
	s_branch .LBB0_147
.LBB0_169:
	s_waitcnt vmcnt(0)
	s_barrier
	s_mov_b64 s[4:5], exec
	v_readlane_b32 s0, v225, 14
	v_readlane_b32 s1, v225, 15
	s_and_b64 s[0:1], s[4:5], s[0:1]
	s_mov_b64 exec, s[0:1]
	s_cbranch_execz .LBB0_179
	s_cmp_eq_u32 s100, 1
	s_cbranch_scc1 .Lgb1_nowb
	buffer_wbl2 sc1
	s_waitcnt vmcnt(0)

; #define RUNPH(n) { run_phase(p, (n), smem); grid.sync(); }
; __global__ void __launch_bounds__(256, 2) mega(Params p) {
;   extern __shared__ __attribute__((aligned(16))) char smem[];
;   cg::grid_group grid = cg::this_grid();
;   RUNPH(0) RUNPH(1) RUNPH(2) RUNPH(3) RUNPH(4) RUNPH(5) RUNPH(6) RUNPH(7) RUNPH(8)
.Lgb1_done:
	s_cmp_lg_u32 s98, 0
	s_cbranch_scc1 .Lgb1_norst
	s_add_u32 s6, s30, 0x3eb38000
	s_addc_u32 s7, s31, 0
	v_mov_b32_e32 v0, 0
	v_mov_b32_e32 v1, 0
	global_atomic_swap v0, v1, s[6:7] offset:128
.Lgb1_norst:
	buffer_inv sc1
	s_waitcnt vmcnt(0)
